# dense item: one static s_setprio 1 for waves 4-7 for the whole item (no per-segment flips)
# baseline (speedup 1.0000x reference)
; #define LAS __attribute__((address_space(3)))
; DI int otid() { int t = threadIdx.x; asm volatile("" : "+v"(t)); return t; }
; template <int DK>
; DI void dense_attn_item(LAS unsigned char* lds, const bf16_t* Qb, int ldq, const bf16_t* Kb, int ldk, const bf16_t* Kpe, const bf16_t* Vt, int nkeys, float sl2, bf16_t* Ob) {
;     const int tid = otid(), lane = tid & 63, wid = tid >> 6, r16 = lane & 15, q4 = lane >> 4;
;     constexpr int KS = DK / 32, KCH = DK / 8, KROW = DK * 2 + 16, KTILE = 64 * KROW, VROW = 144, VTILE = 128 * VROW, NKL = (64 * KCH) / 512;
;     bf16x8 qf[2][KS];
; #pragma unroll
;     for (int qg = 0; qg < 2; ++qg)
; #pragma unroll
;         for (int ks = 0; ks < KS; ++ks) qf[qg][ks] = *(const bf16x8*)(Qb + (size_t)(wid * 32 + qg * 16 + r16) * ldq + ks * 32 + q4 * 8);
;     f32x4 oacc[2][8];
; #pragma unroll
;     for (int qg = 0; qg < 2; ++qg)
; #pragma unroll
;         for (int d = 0; d < 8; ++d) oacc[qg][d] = (f32x4){0.f, 0.f, 0.f, 0.f};
;     float mrun[2] = {-1e30f, -1e30f}, lsum[2] = {0.f, 0.f};
;     u32x4 kst[NKL], vst[2];
;     const int ntiles = nkeys >> 6;
; DI void dense192_item(unsigned char* ws, LAS unsigned char* lds, int b, int h, int q0, int nk) {
;     const size_t rowb = (size_t)b * RB, row0 = rowb + q0;
;     dense_attn_item<192>(lds, (const bf16_t*)(ws + WS_QM) + row0 * 960 + h * 192, 960, (const bf16_t*)(ws + WS_KM) + rowb * 640 + h * 128, 640, (const bf16_t*)(ws + WS_KPE) + rowb * 64,
;                          (const bf16_t*)(ws + WS_VTM) + ((size_t)b * 640 + h * 128) * RB, nk, 0.07216878364870322f * 1.4426950408889634f, (bf16_t*)(ws + WS_YMIX) + row0 * DM + 768 + h * 128);
.LBB0_1146:
	s_mul_hi_u32 s71, s28, 0x66666667
	s_lshr_b32 s71, s71, 4
	s_lshr_b32 s73, s28, 3
	s_mul_i32 s62, s71, 5
	s_sub_u32 s73, s73, s62
	s_and_b32 s62, s28, 7
	s_lshl_b32 s62, s62, 8
	s_mul_i32 s75, s71, 0x900
	s_add_u32 s74, s75, s62
	s_addk_i32 s74, 0x100
	s_mul_i32 s62, s74, 0x780
	s_mul_i32 s63, s73, 0x180
	s_add_u32 s62, s62, s63
	s_add_u32 s62, s62, 0x1a3a0000
	s_add_u32 s10, s50, s62
	s_addc_u32 s11, s51, 0
	s_mul_i32 s62, s75, 0x500
	s_lshl_b32 s63, s73, 8
	s_add_u32 s62, s62, s63
	s_add_u32 s62, s62, 0x1b480000
	s_add_u32 s4, s50, s62
	s_addc_u32 s5, s51, 0
	s_mul_i32 s62, s75, 0x480
	s_add_u32 s62, s62, s63
	s_sub_u32 s76, 0x167ff00, s62
	s_mul_i32 s62, s71, 0x280
	s_lshl_b32 s63, s73, 7
	s_add_u32 s62, s62, s63
	s_mul_i32 s62, s62, 0x1200
	s_add_u32 s62, s62, 0x1bfc0000
	s_add_u32 s8, s50, s62
	s_addc_u32 s9, s51, 0
	s_lshl_b32 s62, s74, 12
	s_lshl_b32 s63, s73, 8
	s_add_u32 s62, s62, s63
	s_add_u32 s62, s62, 0x1d9a0600
	s_add_u32 s20, s50, s62
	s_addc_u32 s21, s51, 0
	s_mov_b32 s22, 0x3dd53b94
	v_mov_b32_e32 v254, s22
	s_mov_b32 s29, 0x41000000
	v_and_b32_e32 v192, 31, v202
	v_bfe_u32 v193, v202, 5, 1
	v_lshrrev_b32_e32 v194, 6, v202
	v_lshl_add_u32 v195, v194, 5, v192
	v_mul_u32_u24_e32 v196, 0x780, v195
	v_lshl_add_u32 v250, v193, 4, v196
	global_load_dwordx4 v[0:3], v250, s[10:11] offset:0
	global_load_dwordx4 v[4:7], v250, s[10:11] offset:32
	global_load_dwordx4 v[8:11], v250, s[10:11] offset:64
	global_load_dwordx4 v[12:15], v250, s[10:11] offset:96
	global_load_dwordx4 v[16:19], v250, s[10:11] offset:128
	global_load_dwordx4 v[20:23], v250, s[10:11] offset:160
	global_load_dwordx4 v[24:27], v250, s[10:11] offset:192
	global_load_dwordx4 v[28:31], v250, s[10:11] offset:224
	global_load_dwordx4 v[32:35], v250, s[10:11] offset:256
	global_load_dwordx4 v[36:39], v250, s[10:11] offset:288
	global_load_dwordx4 v[40:43], v250, s[10:11] offset:320
	global_load_dwordx4 v[44:47], v250, s[10:11] offset:352
	s_mov_b32 s62, 0xaaaaaab
	v_mov_b32_e32 v197, v202
	v_mul_hi_u32 v198, v197, s62
	v_mul_u32_u24_e32 v195, 24, v198
	v_sub_u32_e32 v199, v197, v195
	v_mul_u32_u24_e32 v195, 0x190, v198
	v_lshl_add_u32 v230, v199, 4, v195
	v_cmp_gt_u32_e32 vcc, 16, v199
	v_mul_u32_u24_e32 v195, 0x500, v198
	v_lshlrev_b32_e32 v196, 7, v198
	v_add_u32_e32 v196, s76, v196
	s_nop 1
	v_cndmask_b32_e32 v195, v196, v195, vcc
	v_lshl_add_u32 v224, v199, 4, v195
	v_mov_b32_e32 v195, 0x2000
	v_mov_b32_e32 v196, 0x14000
	v_cndmask_b32_e32 v227, v195, v196, vcc
	v_add_u32_e32 v197, 0x200, v202
	v_mul_hi_u32 v198, v197, s62
	v_mul_u32_u24_e32 v195, 24, v198
	v_sub_u32_e32 v199, v197, v195
	v_mul_u32_u24_e32 v195, 0x190, v198
	v_lshl_add_u32 v231, v199, 4, v195
	v_cmp_gt_u32_e32 vcc, 16, v199
	v_mul_u32_u24_e32 v195, 0x500, v198
	v_lshlrev_b32_e32 v196, 7, v198
	v_add_u32_e32 v196, s76, v196
	s_nop 1
	v_cndmask_b32_e32 v195, v196, v195, vcc
	v_lshl_add_u32 v225, v199, 4, v195
	v_mov_b32_e32 v195, 0x2000
	v_mov_b32_e32 v196, 0x14000
	v_cndmask_b32_e32 v228, v195, v196, vcc
	v_add_u32_e32 v197, 0x400, v202
	v_mul_hi_u32 v198, v197, s62
	v_mul_u32_u24_e32 v195, 24, v198
	v_sub_u32_e32 v199, v197, v195
	v_mul_u32_u24_e32 v195, 0x190, v198
	v_lshl_add_u32 v232, v199, 4, v195
	v_cmp_gt_u32_e32 vcc, 16, v199
	v_mul_u32_u24_e32 v195, 0x500, v198
	v_lshlrev_b32_e32 v196, 7, v198
	v_add_u32_e32 v196, s76, v196
	s_nop 1
	v_cndmask_b32_e32 v195, v196, v195, vcc
	v_lshl_add_u32 v226, v199, 4, v195
	v_mov_b32_e32 v195, 0x2000
	v_mov_b32_e32 v196, 0x14000
	v_cndmask_b32_e32 v229, v195, v196, vcc
	v_mov_b32_e32 v197, v202
	v_lshrrev_b32_e32 v198, 3, v197
	v_and_b32_e32 v199, 7, v197
	v_mul_u32_u24_e32 v195, 0x1200, v198
	v_lshl_add_u32 v233, v199, 4, v195
	v_mul_u32_u24_e32 v195, 0x90, v198
	v_lshl_add_u32 v195, v199, 4, v195
	v_add_u32_e32 v235, 0x12c00, v195
	v_add_u32_e32 v197, 0x200, v202
	v_lshrrev_b32_e32 v198, 3, v197
	v_and_b32_e32 v199, 7, v197
	v_mul_u32_u24_e32 v195, 0x1200, v198
	v_lshl_add_u32 v234, v199, 4, v195
	v_mul_u32_u24_e32 v195, 0x90, v198
	v_lshl_add_u32 v195, v199, 4, v195
	v_add_u32_e32 v236, 0x12c00, v195
	v_mul_u32_u24_e32 v195, 0x190, v192
	v_lshl_add_u32 v237, v193, 4, v195
	v_mul_u32_u24_e32 v195, 0x90, v192
	v_lshl_add_u32 v195, v193, 3, v195
	v_add_u32_e32 v238, 0x12c00, v195
	global_load_dwordx4 v[204:207], v224, s[4:5]
	global_load_dwordx4 v[208:211], v225, s[4:5]
	global_load_dwordx4 v[212:215], v226, s[4:5]
	global_load_dwordx4 v[216:219], v233, s[8:9]
	global_load_dwordx4 v[220:223], v234, s[8:9]
	v_add_u32_e32 v224, v224, v227
	v_add_u32_e32 v225, v225, v228
	v_add_u32_e32 v226, v226, v229
	s_add_u32 s8, s8, 0x80
	s_addc_u32 s9, s9, 0
	v_lshrrev_b32_e32 v195, 6, v202
	s_nop 0
	v_readfirstlane_b32 s62, v195
	s_cmp_ge_u32 s62, 4
	s_cbranch_scc0 dn0_np
	s_setprio 1
; #define LAS __attribute__((address_space(3)))
; template <int DK>
; DI void dense_attn_item(LAS unsigned char* lds, const bf16_t* Qb, int ldq, const bf16_t* Kb, int ldk, const bf16_t* Kpe, const bf16_t* Vt, int nkeys, float sl2, bf16_t* Ob) {
;     ...
;     f32x4 oacc[2][8];
; #pragma unroll
;     for (int qg = 0; qg < 2; ++qg)
; #pragma unroll
;         for (int d = 0; d < 8; ++d) oacc[qg][d] = (f32x4){0.f, 0.f, 0.f, 0.f};
;     float mrun[2] = {-1e30f, -1e30f}, lsum[2] = {0.f, 0.f};
;     u32x4 kst[NKL], vst[2];
;     const int ntiles = nkeys >> 6;
;     ...
;     DA_LOAD(0); DA_STORE(0);
;     __syncthreads();
;     for (int kt = 0; kt < ntiles; ++kt) {
;         const int cur = kt & 1;
;         if (kt + 1 < ntiles) DA_LOAD((kt + 1) * 64);
;         const LAS unsigned char* kb_ = lds + cur * KTILE; const LAS unsigned char* vb_ = lds + 2 * KTILE + cur * VTILE;
; #pragma unroll
;         for (int kc = 0; kc < 2; ++kc) {
;             f32x4 sacc[2][2];
; #pragma unroll
;             for (int kb = 0; kb < 2; ++kb) {
;                 sacc[0][kb] = (f32x4){0.f, 0.f, 0.f, 0.f}; sacc[1][kb] = (f32x4){0.f, 0.f, 0.f, 0.f};
; #pragma unroll
;                 for (int kh = 0; kh < KS / 2; ++kh) {
;                     const bf16x8 k0 = *(const LAS bf16x8*)(kb_ + ((2 * kc + kb) * 16 + r16) * KROW + (2 * kh) * 64 + q4 * 16);
;                     const bf16x8 k1 = *(const LAS bf16x8*)(kb_ + ((2 * kc + kb) * 16 + r16) * KROW + (2 * kh + 1) * 64 + q4 * 16);
;                     __builtin_amdgcn_s_setprio(1);
dn0_np:
	v_mov_b32_e32 v48, 0
	v_mov_b32_e32 v49, 0
	v_mov_b32_e32 v50, 0
	v_mov_b32_e32 v51, 0
	v_mov_b32_e32 v52, 0
	v_mov_b32_e32 v53, 0
	v_mov_b32_e32 v54, 0
	v_mov_b32_e32 v55, 0
	v_mov_b32_e32 v56, 0
	v_mov_b32_e32 v57, 0
	v_mov_b32_e32 v58, 0
	v_mov_b32_e32 v59, 0
	v_mov_b32_e32 v60, 0
	v_mov_b32_e32 v61, 0
	v_mov_b32_e32 v62, 0
	v_mov_b32_e32 v63, 0
	v_mov_b32_e32 v64, 0
	v_mov_b32_e32 v65, 0
	v_mov_b32_e32 v66, 0
	v_mov_b32_e32 v67, 0
	v_mov_b32_e32 v68, 0
	v_mov_b32_e32 v69, 0
	v_mov_b32_e32 v70, 0
	v_mov_b32_e32 v71, 0
	v_mov_b32_e32 v72, 0
	v_mov_b32_e32 v73, 0
	v_mov_b32_e32 v74, 0
	v_mov_b32_e32 v75, 0
	v_mov_b32_e32 v76, 0
	v_mov_b32_e32 v77, 0
	v_mov_b32_e32 v78, 0
	v_mov_b32_e32 v79, 0
	v_mov_b32_e32 v80, 0
	v_mov_b32_e32 v81, 0
	v_mov_b32_e32 v82, 0
	v_mov_b32_e32 v83, 0
	v_mov_b32_e32 v84, 0
	v_mov_b32_e32 v85, 0
	v_mov_b32_e32 v86, 0
	v_mov_b32_e32 v87, 0
	v_mov_b32_e32 v88, 0
	v_mov_b32_e32 v89, 0
	v_mov_b32_e32 v90, 0
	v_mov_b32_e32 v91, 0
	v_mov_b32_e32 v92, 0
	v_mov_b32_e32 v93, 0
	v_mov_b32_e32 v94, 0
	v_mov_b32_e32 v95, 0
	v_mov_b32_e32 v96, 0
	v_mov_b32_e32 v97, 0
	v_mov_b32_e32 v98, 0
	v_mov_b32_e32 v99, 0
	v_mov_b32_e32 v100, 0
	v_mov_b32_e32 v101, 0
	v_mov_b32_e32 v102, 0
	v_mov_b32_e32 v103, 0
	v_mov_b32_e32 v104, 0
	v_mov_b32_e32 v105, 0
	v_mov_b32_e32 v106, 0
	v_mov_b32_e32 v107, 0
	v_mov_b32_e32 v108, 0
	v_mov_b32_e32 v109, 0
	v_mov_b32_e32 v110, 0
	v_mov_b32_e32 v111, 0
	v_mov_b32_e32 v242, 0xf149f2ca
	v_mov_b32_e32 v244, 0
	s_waitcnt vmcnt(0)
	v_lshl_add_u32 v195, v194, 5, v192
	v_lshlrev_b32_e32 v195, 12, v195
	v_lshl_add_u32 v250, v193, 3, v195
	ds_write_b128 v230, v[204:207]
	ds_write_b128 v231, v[208:211]
	ds_write_b128 v232, v[212:215]
	ds_write_b128 v235, v[216:219]
	ds_write_b128 v236, v[220:223]
	s_waitcnt lgkmcnt(0)
	global_load_dwordx4 v[204:207], v224, s[4:5]
	global_load_dwordx4 v[208:211], v225, s[4:5]
	global_load_dwordx4 v[212:215], v226, s[4:5]
	global_load_dwordx4 v[216:219], v233, s[8:9]
	global_load_dwordx4 v[220:223], v234, s[8:9]
	s_barrier
	v_mov_b32_e32 v239, v237
	ds_read_b128 v[144:147], v239 offset:0
	ds_read_b128 v[148:151], v239 offset:32
	ds_read_b128 v[152:155], v239 offset:64
	ds_read_b128 v[156:159], v239 offset:96
	ds_read_b128 v[160:163], v239 offset:128
	ds_read_b128 v[164:167], v239 offset:160
	s_waitcnt lgkmcnt(5)
	v_mfma_f32_32x32x16_bf16 v[112:127], v[144:147], v[0:3], 0
	ds_read_b128 v[144:147], v239 offset:192
	s_waitcnt lgkmcnt(5)
	v_mfma_f32_32x32x16_bf16 v[112:127], v[148:151], v[4:7], v[112:127]
	ds_read_b128 v[148:151], v239 offset:224
	s_waitcnt lgkmcnt(5)
	v_mfma_f32_32x32x16_bf16 v[112:127], v[152:155], v[8:11], v[112:127]
	ds_read_b128 v[152:155], v239 offset:256
	s_waitcnt lgkmcnt(5)
	v_mfma_f32_32x32x16_bf16 v[112:127], v[156:159], v[12:15], v[112:127]
	ds_read_b128 v[156:159], v239 offset:288
	s_waitcnt lgkmcnt(5)
	v_mfma_f32_32x32x16_bf16 v[112:127], v[160:163], v[16:19], v[112:127]
	ds_read_b128 v[160:163], v239 offset:320
	s_waitcnt lgkmcnt(5)
	v_mfma_f32_32x32x16_bf16 v[112:127], v[164:167], v[20:23], v[112:127]
	ds_read_b128 v[164:167], v239 offset:352
	s_waitcnt lgkmcnt(5)
	v_mfma_f32_32x32x16_bf16 v[112:127], v[144:147], v[24:27], v[112:127]
	s_waitcnt lgkmcnt(4)
	v_mfma_f32_32x32x16_bf16 v[112:127], v[148:151], v[28:31], v[112:127]
	s_waitcnt lgkmcnt(3)
	v_mfma_f32_32x32x16_bf16 v[112:127], v[152:155], v[32:35], v[112:127]
	s_waitcnt lgkmcnt(2)
	v_mfma_f32_32x32x16_bf16 v[112:127], v[156:159], v[36:39], v[112:127]
	s_waitcnt lgkmcnt(1)
	v_mfma_f32_32x32x16_bf16 v[112:127], v[160:163], v[40:43], v[112:127]
	s_waitcnt lgkmcnt(0)
	v_mfma_f32_32x32x16_bf16 v[112:127], v[164:167], v[44:47], v[112:127]
	ds_read_b128 v[144:147], v239 offset:12800
	ds_read_b128 v[148:151], v239 offset:12832
	ds_read_b128 v[152:155], v239 offset:12864
	ds_read_b128 v[156:159], v239 offset:12896
	ds_read_b128 v[160:163], v239 offset:12928
	ds_read_b128 v[164:167], v239 offset:12960
	s_mov_b32 s23, 0
	s_mov_b32 s27, 0

; #define LAS __attribute__((address_space(3)))
; DI unsigned xb_add(unsigned* p, unsigned v) { return __hip_atomic_fetch_add(p, v, __ATOMIC_RELAXED, __HIP_MEMORY_SCOPE_AGENT); }
; DI void st_bf16x4(bf16_t* p, f32x4 v) { u32x2 w; w.x = cvt_pk_bf16(v[0], v[1]); w.y = cvt_pk_bf16(v[2], v[3]); *(u32x2*)p = w; }
; DI int next_item(unsigned* ctr, volatile LAS int* slot) {
;     __syncthreads();
;     if (threadIdx.x == 0) *slot = (int)xb_add(ctr, 1u);
;     __syncthreads();
;     return *slot;
; template <int DK>
; DI void dense_attn_item(LAS unsigned char* lds, const bf16_t* Qb, int ldq, const bf16_t* Kb, int ldk, const bf16_t* Kpe, const bf16_t* Vt, int nkeys, float sl2, bf16_t* Ob) {
;     ...
; #pragma unroll
;     for (int qg = 0; qg < 2; ++qg) {
;         float l = lsum[qg]; l += __shfl_xor(l, 16); l += __shfl_xor(l, 32);
;         const float inv = 1.f / l;
;         bf16_t* op = Ob + (size_t)(wid * 32 + qg * 16 + r16) * DM + q4 * 4;
; #pragma unroll
;         for (int d = 0; d < 8; ++d) st_bf16x4(op + d * 16, oacc[qg][d] * inv);
;     }
dn0_jn2:
	s_mov_b32 s27, s57
	s_add_u32 s23, s23, 1
	s_cmp_lt_u32 s23, 36
	s_cbranch_scc1 dn0_top
	s_waitcnt vmcnt(0) lgkmcnt(0)
	v_mov_b32_e32 v193, v244
	v_mov_b32_e32 v192, v244
	s_nop 1
	v_permlane32_swap_b32_e32 v193, v192
	v_add_f32_e32 v193, v193, v192
	v_rcp_f32_e32 v192, v193
	s_nop 0
	v_fma_f32 v193, -v193, v192, 1.0
	v_fma_f32 v246, v193, v192, v192
	v_pk_mul_f32 v[48:49], v[48:49], v[246:247] op_sel_hi:[1,0]
	v_pk_mul_f32 v[50:51], v[50:51], v[246:247] op_sel_hi:[1,0]
	v_cvt_pk_bf16_f32 v48, v48, v49
	v_cvt_pk_bf16_f32 v49, v50, v51
	global_store_dwordx2 v250, v[48:49], s[20:21] offset:0
	v_pk_mul_f32 v[52:53], v[52:53], v[246:247] op_sel_hi:[1,0]
	v_pk_mul_f32 v[54:55], v[54:55], v[246:247] op_sel_hi:[1,0]
	v_cvt_pk_bf16_f32 v52, v52, v53
	v_cvt_pk_bf16_f32 v53, v54, v55
	global_store_dwordx2 v250, v[52:53], s[20:21] offset:16
	v_pk_mul_f32 v[56:57], v[56:57], v[246:247] op_sel_hi:[1,0]
	v_pk_mul_f32 v[58:59], v[58:59], v[246:247] op_sel_hi:[1,0]
	v_cvt_pk_bf16_f32 v56, v56, v57
	v_cvt_pk_bf16_f32 v57, v58, v59
	global_store_dwordx2 v250, v[56:57], s[20:21] offset:32
	v_pk_mul_f32 v[60:61], v[60:61], v[246:247] op_sel_hi:[1,0]
	v_pk_mul_f32 v[62:63], v[62:63], v[246:247] op_sel_hi:[1,0]
	v_cvt_pk_bf16_f32 v60, v60, v61
	v_cvt_pk_bf16_f32 v61, v62, v63
	global_store_dwordx2 v250, v[60:61], s[20:21] offset:48
	v_pk_mul_f32 v[64:65], v[64:65], v[246:247] op_sel_hi:[1,0]
	v_pk_mul_f32 v[66:67], v[66:67], v[246:247] op_sel_hi:[1,0]
	v_cvt_pk_bf16_f32 v64, v64, v65
	v_cvt_pk_bf16_f32 v65, v66, v67
	global_store_dwordx2 v250, v[64:65], s[20:21] offset:64
	v_pk_mul_f32 v[68:69], v[68:69], v[246:247] op_sel_hi:[1,0]
	v_pk_mul_f32 v[70:71], v[70:71], v[246:247] op_sel_hi:[1,0]
	v_cvt_pk_bf16_f32 v68, v68, v69
	v_cvt_pk_bf16_f32 v69, v70, v71
	global_store_dwordx2 v250, v[68:69], s[20:21] offset:80
	v_pk_mul_f32 v[72:73], v[72:73], v[246:247] op_sel_hi:[1,0]
	v_pk_mul_f32 v[74:75], v[74:75], v[246:247] op_sel_hi:[1,0]
	v_cvt_pk_bf16_f32 v72, v72, v73
	v_cvt_pk_bf16_f32 v73, v74, v75
	global_store_dwordx2 v250, v[72:73], s[20:21] offset:96
	v_pk_mul_f32 v[76:77], v[76:77], v[246:247] op_sel_hi:[1,0]
	v_pk_mul_f32 v[78:79], v[78:79], v[246:247] op_sel_hi:[1,0]
	v_cvt_pk_bf16_f32 v76, v76, v77
	v_cvt_pk_bf16_f32 v77, v78, v79
	global_store_dwordx2 v250, v[76:77], s[20:21] offset:112
	v_pk_mul_f32 v[80:81], v[80:81], v[246:247] op_sel_hi:[1,0]
	v_pk_mul_f32 v[82:83], v[82:83], v[246:247] op_sel_hi:[1,0]
	v_cvt_pk_bf16_f32 v80, v80, v81
	v_cvt_pk_bf16_f32 v81, v82, v83
	global_store_dwordx2 v250, v[80:81], s[20:21] offset:128
	v_pk_mul_f32 v[84:85], v[84:85], v[246:247] op_sel_hi:[1,0]
	v_pk_mul_f32 v[86:87], v[86:87], v[246:247] op_sel_hi:[1,0]
	v_cvt_pk_bf16_f32 v84, v84, v85
	v_cvt_pk_bf16_f32 v85, v86, v87
	global_store_dwordx2 v250, v[84:85], s[20:21] offset:144
	v_pk_mul_f32 v[88:89], v[88:89], v[246:247] op_sel_hi:[1,0]
	v_pk_mul_f32 v[90:91], v[90:91], v[246:247] op_sel_hi:[1,0]
	v_cvt_pk_bf16_f32 v88, v88, v89
	v_cvt_pk_bf16_f32 v89, v90, v91
	global_store_dwordx2 v250, v[88:89], s[20:21] offset:160
	v_pk_mul_f32 v[92:93], v[92:93], v[246:247] op_sel_hi:[1,0]
	v_pk_mul_f32 v[94:95], v[94:95], v[246:247] op_sel_hi:[1,0]
	v_cvt_pk_bf16_f32 v92, v92, v93
	v_cvt_pk_bf16_f32 v93, v94, v95
	global_store_dwordx2 v250, v[92:93], s[20:21] offset:176
	v_pk_mul_f32 v[96:97], v[96:97], v[246:247] op_sel_hi:[1,0]
	v_pk_mul_f32 v[98:99], v[98:99], v[246:247] op_sel_hi:[1,0]
	v_cvt_pk_bf16_f32 v96, v96, v97
	v_cvt_pk_bf16_f32 v97, v98, v99
	global_store_dwordx2 v250, v[96:97], s[20:21] offset:192
	v_pk_mul_f32 v[100:101], v[100:101], v[246:247] op_sel_hi:[1,0]
	v_pk_mul_f32 v[102:103], v[102:103], v[246:247] op_sel_hi:[1,0]
	v_cvt_pk_bf16_f32 v100, v100, v101
	v_cvt_pk_bf16_f32 v101, v102, v103
	global_store_dwordx2 v250, v[100:101], s[20:21] offset:208
	v_pk_mul_f32 v[104:105], v[104:105], v[246:247] op_sel_hi:[1,0]
	v_pk_mul_f32 v[106:107], v[106:107], v[246:247] op_sel_hi:[1,0]
	v_cvt_pk_bf16_f32 v104, v104, v105
	v_cvt_pk_bf16_f32 v105, v106, v107
	global_store_dwordx2 v250, v[104:105], s[20:21] offset:224
	v_pk_mul_f32 v[108:109], v[108:109], v[246:247] op_sel_hi:[1,0]
	v_pk_mul_f32 v[110:111], v[110:111], v[246:247] op_sel_hi:[1,0]
	v_cvt_pk_bf16_f32 v108, v108, v109
	v_cvt_pk_bf16_f32 v109, v110, v111
	global_store_dwordx2 v250, v[108:109], s[20:21] offset:240
	s_setprio 0
	v_mov_b32_e32 v133, 0
	s_waitcnt vmcnt(0)
	s_barrier
	s_and_saveexec_b64 s[0:1], s[24:25]
	s_cbranch_execz .LBB0_1145
	s_mov_b64 s[8:9], exec
	v_mbcnt_lo_u32_b32 v0, s8, 0
	v_mbcnt_hi_u32_b32 v0, s9, v0
	v_cmp_eq_u32_e32 vcc, 0, v0
	s_and_saveexec_b64 s[6:7], vcc
	s_cbranch_execz .LBB0_1144
	s_bcnt1_i32_b64 s8, s[8:9]
	v_mov_b32_e32 v1, s8
	global_atomic_add v1, v133, v1, s[42:43] sc0
	s_branch .LBB0_1144

; #define LAS __attribute__((address_space(3)))
; DI int otid() { int t = threadIdx.x; asm volatile("" : "+v"(t)); return t; }
; template <int DK>
; DI void dense_attn_item(LAS unsigned char* lds, const bf16_t* Qb, int ldq, const bf16_t* Kb, int ldk, const bf16_t* Kpe, const bf16_t* Vt, int nkeys, float sl2, bf16_t* Ob) {
;     const int tid = otid(), lane = tid & 63, wid = tid >> 6, r16 = lane & 15, q4 = lane >> 4;
;     constexpr int KS = DK / 32, KCH = DK / 8, KROW = DK * 2 + 16, KTILE = 64 * KROW, VROW = 144, VTILE = 128 * VROW, NKL = (64 * KCH) / 512;
;     bf16x8 qf[2][KS];
; #pragma unroll
;     for (int qg = 0; qg < 2; ++qg)
; #pragma unroll
;         for (int ks = 0; ks < KS; ++ks) qf[qg][ks] = *(const bf16x8*)(Qb + (size_t)(wid * 32 + qg * 16 + r16) * ldq + ks * 32 + q4 * 8);
;     f32x4 oacc[2][8];
; #pragma unroll
;     for (int qg = 0; qg < 2; ++qg)
; #pragma unroll
;         for (int d = 0; d < 8; ++d) oacc[qg][d] = (f32x4){0.f, 0.f, 0.f, 0.f};
;     float mrun[2] = {-1e30f, -1e30f}, lsum[2] = {0.f, 0.f};
;     u32x4 kst[NKL], vst[2];
;     const int ntiles = nkeys >> 6;
; DI void dense192_item(unsigned char* ws, LAS unsigned char* lds, int b, int h, int q0, int nk) {
;     const size_t rowb = (size_t)b * RB, row0 = rowb + q0;
;     dense_attn_item<192>(lds, (const bf16_t*)(ws + WS_QM) + row0 * 960 + h * 192, 960, (const bf16_t*)(ws + WS_KM) + rowb * 640 + h * 128, 640, (const bf16_t*)(ws + WS_KPE) + rowb * 64,
;                          (const bf16_t*)(ws + WS_VTM) + ((size_t)b * 640 + h * 128) * RB, nk, 0.07216878364870322f * 1.4426950408889634f, (bf16_t*)(ws + WS_YMIX) + row0 * DM + 768 + h * 128);
.LBB0_2593:
	s_mul_hi_u32 s71, s0, 0x66666667
	s_lshr_b32 s71, s71, 4
	s_lshr_b32 s73, s0, 3
	s_mul_i32 s62, s71, 5
	s_sub_u32 s73, s73, s62
	s_and_b32 s62, s0, 7
	s_lshl_b32 s62, s62, 8
	s_mul_i32 s75, s71, 0x900
	s_add_u32 s74, s75, s62
	s_addk_i32 s74, 0x100
	s_mul_i32 s62, s74, 0x780
	s_mul_i32 s63, s73, 0x180
	s_add_u32 s62, s62, s63
	s_add_u32 s62, s62, 0x1a3a0000
	s_add_u32 s10, s50, s62
	s_addc_u32 s11, s51, 0
	s_mul_i32 s62, s75, 0x500
	s_lshl_b32 s63, s73, 8
	s_add_u32 s62, s62, s63
	s_add_u32 s62, s62, 0x1b480000
	s_add_u32 s4, s50, s62
	s_addc_u32 s5, s51, 0
	s_mul_i32 s62, s75, 0x480
	s_add_u32 s62, s62, s63
	s_sub_u32 s76, 0x167ff00, s62
	s_mul_i32 s62, s71, 0x280
	s_lshl_b32 s63, s73, 7
	s_add_u32 s62, s62, s63
	s_mul_i32 s62, s62, 0x1200
	s_add_u32 s62, s62, 0x1bfc0000
	s_add_u32 s8, s50, s62
	s_addc_u32 s9, s51, 0
	s_lshl_b32 s62, s74, 12
	s_lshl_b32 s63, s73, 8
	s_add_u32 s62, s62, s63
	s_add_u32 s62, s62, 0x1d9a0600
	s_add_u32 s20, s50, s62
	s_addc_u32 s21, s51, 0
	s_mov_b32 s22, 0x3dd53b94
	v_mov_b32_e32 v254, s22
	s_mov_b32 s29, 0x41000000
	v_and_b32_e32 v192, 31, v202
	v_bfe_u32 v193, v202, 5, 1
	v_lshrrev_b32_e32 v194, 6, v202
	v_lshl_add_u32 v195, v194, 5, v192
	v_mul_u32_u24_e32 v196, 0x780, v195
	v_lshl_add_u32 v250, v193, 4, v196
	global_load_dwordx4 v[0:3], v250, s[10:11] offset:0
	global_load_dwordx4 v[4:7], v250, s[10:11] offset:32
	global_load_dwordx4 v[8:11], v250, s[10:11] offset:64
	global_load_dwordx4 v[12:15], v250, s[10:11] offset:96
	global_load_dwordx4 v[16:19], v250, s[10:11] offset:128
	global_load_dwordx4 v[20:23], v250, s[10:11] offset:160
	global_load_dwordx4 v[24:27], v250, s[10:11] offset:192
	global_load_dwordx4 v[28:31], v250, s[10:11] offset:224
	global_load_dwordx4 v[32:35], v250, s[10:11] offset:256
	global_load_dwordx4 v[36:39], v250, s[10:11] offset:288
	global_load_dwordx4 v[40:43], v250, s[10:11] offset:320
	global_load_dwordx4 v[44:47], v250, s[10:11] offset:352
	s_mov_b32 s62, 0xaaaaaab
	v_mov_b32_e32 v197, v202
	v_mul_hi_u32 v198, v197, s62
	v_mul_u32_u24_e32 v195, 24, v198
	v_sub_u32_e32 v199, v197, v195
	v_mul_u32_u24_e32 v195, 0x190, v198
	v_lshl_add_u32 v230, v199, 4, v195
	v_cmp_gt_u32_e32 vcc, 16, v199
	v_mul_u32_u24_e32 v195, 0x500, v198
	v_lshlrev_b32_e32 v196, 7, v198
	v_add_u32_e32 v196, s76, v196
	s_nop 1
	v_cndmask_b32_e32 v195, v196, v195, vcc
	v_lshl_add_u32 v224, v199, 4, v195
	v_mov_b32_e32 v195, 0x2000
	v_mov_b32_e32 v196, 0x14000
	v_cndmask_b32_e32 v227, v195, v196, vcc
	v_add_u32_e32 v197, 0x200, v202
	v_mul_hi_u32 v198, v197, s62
	v_mul_u32_u24_e32 v195, 24, v198
	v_sub_u32_e32 v199, v197, v195
	v_mul_u32_u24_e32 v195, 0x190, v198
	v_lshl_add_u32 v231, v199, 4, v195
	v_cmp_gt_u32_e32 vcc, 16, v199
	v_mul_u32_u24_e32 v195, 0x500, v198
	v_lshlrev_b32_e32 v196, 7, v198
	v_add_u32_e32 v196, s76, v196
	s_nop 1
	v_cndmask_b32_e32 v195, v196, v195, vcc
	v_lshl_add_u32 v225, v199, 4, v195
	v_mov_b32_e32 v195, 0x2000
	v_mov_b32_e32 v196, 0x14000
	v_cndmask_b32_e32 v228, v195, v196, vcc
	v_add_u32_e32 v197, 0x400, v202
	v_mul_hi_u32 v198, v197, s62
	v_mul_u32_u24_e32 v195, 24, v198
	v_sub_u32_e32 v199, v197, v195
	v_mul_u32_u24_e32 v195, 0x190, v198
	v_lshl_add_u32 v232, v199, 4, v195
	v_cmp_gt_u32_e32 vcc, 16, v199
	v_mul_u32_u24_e32 v195, 0x500, v198
	v_lshlrev_b32_e32 v196, 7, v198
	v_add_u32_e32 v196, s76, v196
	s_nop 1
	v_cndmask_b32_e32 v195, v196, v195, vcc
	v_lshl_add_u32 v226, v199, 4, v195
	v_mov_b32_e32 v195, 0x2000
	v_mov_b32_e32 v196, 0x14000
	v_cndmask_b32_e32 v229, v195, v196, vcc
	v_mov_b32_e32 v197, v202
	v_lshrrev_b32_e32 v198, 3, v197
	v_and_b32_e32 v199, 7, v197
	v_mul_u32_u24_e32 v195, 0x1200, v198
	v_lshl_add_u32 v233, v199, 4, v195
	v_mul_u32_u24_e32 v195, 0x90, v198
	v_lshl_add_u32 v195, v199, 4, v195
	v_add_u32_e32 v235, 0x12c00, v195
	v_add_u32_e32 v197, 0x200, v202
	v_lshrrev_b32_e32 v198, 3, v197
	v_and_b32_e32 v199, 7, v197
	v_mul_u32_u24_e32 v195, 0x1200, v198
	v_lshl_add_u32 v234, v199, 4, v195
	v_mul_u32_u24_e32 v195, 0x90, v198
	v_lshl_add_u32 v195, v199, 4, v195
	v_add_u32_e32 v236, 0x12c00, v195
	v_mul_u32_u24_e32 v195, 0x190, v192
	v_lshl_add_u32 v237, v193, 4, v195
	v_mul_u32_u24_e32 v195, 0x90, v192
	v_lshl_add_u32 v195, v193, 3, v195
	v_add_u32_e32 v238, 0x12c00, v195
	global_load_dwordx4 v[204:207], v224, s[4:5]
	global_load_dwordx4 v[208:211], v225, s[4:5]
	global_load_dwordx4 v[212:215], v226, s[4:5]
	global_load_dwordx4 v[216:219], v233, s[8:9]
	global_load_dwordx4 v[220:223], v234, s[8:9]
	v_add_u32_e32 v224, v224, v227
	v_add_u32_e32 v225, v225, v228
	v_add_u32_e32 v226, v226, v229
	s_add_u32 s8, s8, 0x80
	s_addc_u32 s9, s9, 0
	v_lshrrev_b32_e32 v195, 6, v202
	s_nop 0
	v_readfirstlane_b32 s62, v195
	s_cmp_ge_u32 s62, 4
	s_cbranch_scc0 dn1_np
	s_setprio 1
; #define LAS __attribute__((address_space(3)))
; template <int DK>
; DI void dense_attn_item(LAS unsigned char* lds, const bf16_t* Qb, int ldq, const bf16_t* Kb, int ldk, const bf16_t* Kpe, const bf16_t* Vt, int nkeys, float sl2, bf16_t* Ob) {
;     ...
;     f32x4 oacc[2][8];
; #pragma unroll
;     for (int qg = 0; qg < 2; ++qg)
; #pragma unroll
;         for (int d = 0; d < 8; ++d) oacc[qg][d] = (f32x4){0.f, 0.f, 0.f, 0.f};
;     float mrun[2] = {-1e30f, -1e30f}, lsum[2] = {0.f, 0.f};
;     u32x4 kst[NKL], vst[2];
;     const int ntiles = nkeys >> 6;
;     ...
;     DA_LOAD(0); DA_STORE(0);
;     __syncthreads();
;     for (int kt = 0; kt < ntiles; ++kt) {
;         const int cur = kt & 1;
;         if (kt + 1 < ntiles) DA_LOAD((kt + 1) * 64);
;         const LAS unsigned char* kb_ = lds + cur * KTILE; const LAS unsigned char* vb_ = lds + 2 * KTILE + cur * VTILE;
; #pragma unroll
;         for (int kc = 0; kc < 2; ++kc) {
;             f32x4 sacc[2][2];
; #pragma unroll
;             for (int kb = 0; kb < 2; ++kb) {
;                 sacc[0][kb] = (f32x4){0.f, 0.f, 0.f, 0.f}; sacc[1][kb] = (f32x4){0.f, 0.f, 0.f, 0.f};
; #pragma unroll
;                 for (int kh = 0; kh < KS / 2; ++kh) {
;                     const bf16x8 k0 = *(const LAS bf16x8*)(kb_ + ((2 * kc + kb) * 16 + r16) * KROW + (2 * kh) * 64 + q4 * 16);
;                     const bf16x8 k1 = *(const LAS bf16x8*)(kb_ + ((2 * kc + kb) * 16 + r16) * KROW + (2 * kh + 1) * 64 + q4 * 16);
;                     __builtin_amdgcn_s_setprio(1);
dn1_np:
	v_mov_b32_e32 v48, 0
	v_mov_b32_e32 v49, 0
	v_mov_b32_e32 v50, 0
	v_mov_b32_e32 v51, 0
	v_mov_b32_e32 v52, 0
	v_mov_b32_e32 v53, 0
	v_mov_b32_e32 v54, 0
	v_mov_b32_e32 v55, 0
	v_mov_b32_e32 v56, 0
	v_mov_b32_e32 v57, 0
	v_mov_b32_e32 v58, 0
	v_mov_b32_e32 v59, 0
	v_mov_b32_e32 v60, 0
	v_mov_b32_e32 v61, 0
	v_mov_b32_e32 v62, 0
	v_mov_b32_e32 v63, 0
	v_mov_b32_e32 v64, 0
	v_mov_b32_e32 v65, 0
	v_mov_b32_e32 v66, 0
	v_mov_b32_e32 v67, 0
	v_mov_b32_e32 v68, 0
	v_mov_b32_e32 v69, 0
	v_mov_b32_e32 v70, 0
	v_mov_b32_e32 v71, 0
	v_mov_b32_e32 v72, 0
	v_mov_b32_e32 v73, 0
	v_mov_b32_e32 v74, 0
	v_mov_b32_e32 v75, 0
	v_mov_b32_e32 v76, 0
	v_mov_b32_e32 v77, 0
	v_mov_b32_e32 v78, 0
	v_mov_b32_e32 v79, 0
	v_mov_b32_e32 v80, 0
	v_mov_b32_e32 v81, 0
	v_mov_b32_e32 v82, 0
	v_mov_b32_e32 v83, 0
	v_mov_b32_e32 v84, 0
	v_mov_b32_e32 v85, 0
	v_mov_b32_e32 v86, 0
	v_mov_b32_e32 v87, 0
	v_mov_b32_e32 v88, 0
	v_mov_b32_e32 v89, 0
	v_mov_b32_e32 v90, 0
	v_mov_b32_e32 v91, 0
	v_mov_b32_e32 v92, 0
	v_mov_b32_e32 v93, 0
	v_mov_b32_e32 v94, 0
	v_mov_b32_e32 v95, 0
	v_mov_b32_e32 v96, 0
	v_mov_b32_e32 v97, 0
	v_mov_b32_e32 v98, 0
	v_mov_b32_e32 v99, 0
	v_mov_b32_e32 v100, 0
	v_mov_b32_e32 v101, 0
	v_mov_b32_e32 v102, 0
	v_mov_b32_e32 v103, 0
	v_mov_b32_e32 v104, 0
	v_mov_b32_e32 v105, 0
	v_mov_b32_e32 v106, 0
	v_mov_b32_e32 v107, 0
	v_mov_b32_e32 v108, 0
	v_mov_b32_e32 v109, 0
	v_mov_b32_e32 v110, 0
	v_mov_b32_e32 v111, 0
	v_mov_b32_e32 v242, 0xf149f2ca
	v_mov_b32_e32 v244, 0
	s_waitcnt vmcnt(0)
	v_lshl_add_u32 v195, v194, 5, v192
	v_lshlrev_b32_e32 v195, 12, v195
	v_lshl_add_u32 v250, v193, 3, v195
	ds_write_b128 v230, v[204:207]
	ds_write_b128 v231, v[208:211]
	ds_write_b128 v232, v[212:215]
	ds_write_b128 v235, v[216:219]
	ds_write_b128 v236, v[220:223]
	s_waitcnt lgkmcnt(0)
	global_load_dwordx4 v[204:207], v224, s[4:5]
	global_load_dwordx4 v[208:211], v225, s[4:5]
	global_load_dwordx4 v[212:215], v226, s[4:5]
	global_load_dwordx4 v[216:219], v233, s[8:9]
	global_load_dwordx4 v[220:223], v234, s[8:9]
	s_barrier
	v_mov_b32_e32 v239, v237
	ds_read_b128 v[144:147], v239 offset:0
	ds_read_b128 v[148:151], v239 offset:32
	ds_read_b128 v[152:155], v239 offset:64
	ds_read_b128 v[156:159], v239 offset:96
	ds_read_b128 v[160:163], v239 offset:128
	ds_read_b128 v[164:167], v239 offset:160
	s_waitcnt lgkmcnt(5)
	v_mfma_f32_32x32x16_bf16 v[112:127], v[144:147], v[0:3], 0
	ds_read_b128 v[144:147], v239 offset:192
	s_waitcnt lgkmcnt(5)
	v_mfma_f32_32x32x16_bf16 v[112:127], v[148:151], v[4:7], v[112:127]
	ds_read_b128 v[148:151], v239 offset:224
	s_waitcnt lgkmcnt(5)
	v_mfma_f32_32x32x16_bf16 v[112:127], v[152:155], v[8:11], v[112:127]
	ds_read_b128 v[152:155], v239 offset:256
	s_waitcnt lgkmcnt(5)
	v_mfma_f32_32x32x16_bf16 v[112:127], v[156:159], v[12:15], v[112:127]
	ds_read_b128 v[156:159], v239 offset:288
	s_waitcnt lgkmcnt(5)
	v_mfma_f32_32x32x16_bf16 v[112:127], v[160:163], v[16:19], v[112:127]
	ds_read_b128 v[160:163], v239 offset:320
	s_waitcnt lgkmcnt(5)
	v_mfma_f32_32x32x16_bf16 v[112:127], v[164:167], v[20:23], v[112:127]
	ds_read_b128 v[164:167], v239 offset:352
	s_waitcnt lgkmcnt(5)
	v_mfma_f32_32x32x16_bf16 v[112:127], v[144:147], v[24:27], v[112:127]
	s_waitcnt lgkmcnt(4)
	v_mfma_f32_32x32x16_bf16 v[112:127], v[148:151], v[28:31], v[112:127]
	s_waitcnt lgkmcnt(3)
	v_mfma_f32_32x32x16_bf16 v[112:127], v[152:155], v[32:35], v[112:127]
	s_waitcnt lgkmcnt(2)
	v_mfma_f32_32x32x16_bf16 v[112:127], v[156:159], v[36:39], v[112:127]
	s_waitcnt lgkmcnt(1)
	v_mfma_f32_32x32x16_bf16 v[112:127], v[160:163], v[40:43], v[112:127]
	s_waitcnt lgkmcnt(0)
	v_mfma_f32_32x32x16_bf16 v[112:127], v[164:167], v[44:47], v[112:127]
	ds_read_b128 v[144:147], v239 offset:12800
	ds_read_b128 v[148:151], v239 offset:12832
	ds_read_b128 v[152:155], v239 offset:12864
	ds_read_b128 v[156:159], v239 offset:12896
	ds_read_b128 v[160:163], v239 offset:12928
	ds_read_b128 v[164:167], v239 offset:12960
	s_mov_b32 s23, 0
	s_mov_b32 s27, 0

; #define LAS __attribute__((address_space(3)))
; DI unsigned xb_add(unsigned* p, unsigned v) { return __hip_atomic_fetch_add(p, v, __ATOMIC_RELAXED, __HIP_MEMORY_SCOPE_AGENT); }
; DI void st_bf16x4(bf16_t* p, f32x4 v) { u32x2 w; w.x = cvt_pk_bf16(v[0], v[1]); w.y = cvt_pk_bf16(v[2], v[3]); *(u32x2*)p = w; }
; DI int next_item(unsigned* ctr, volatile LAS int* slot) {
;     __syncthreads();
;     if (threadIdx.x == 0) *slot = (int)xb_add(ctr, 1u);
;     __syncthreads();
;     return *slot;
; template <int DK>
; DI void dense_attn_item(LAS unsigned char* lds, const bf16_t* Qb, int ldq, const bf16_t* Kb, int ldk, const bf16_t* Kpe, const bf16_t* Vt, int nkeys, float sl2, bf16_t* Ob) {
;     ...
; #pragma unroll
;     for (int qg = 0; qg < 2; ++qg) {
;         float l = lsum[qg]; l += __shfl_xor(l, 16); l += __shfl_xor(l, 32);
;         const float inv = 1.f / l;
;         bf16_t* op = Ob + (size_t)(wid * 32 + qg * 16 + r16) * DM + q4 * 4;
; #pragma unroll
;         for (int d = 0; d < 8; ++d) st_bf16x4(op + d * 16, oacc[qg][d] * inv);
;     }
dn1_jn2:
	s_mov_b32 s27, s57
	s_add_u32 s23, s23, 1
	s_cmp_lt_u32 s23, 36
	s_cbranch_scc1 dn1_top
	s_waitcnt vmcnt(0) lgkmcnt(0)
	v_mov_b32_e32 v193, v244
	v_mov_b32_e32 v192, v244
	s_nop 1
	v_permlane32_swap_b32_e32 v193, v192
	v_add_f32_e32 v193, v193, v192
	v_rcp_f32_e32 v192, v193
	s_nop 0
	v_fma_f32 v193, -v193, v192, 1.0
	v_fma_f32 v246, v193, v192, v192
	v_pk_mul_f32 v[48:49], v[48:49], v[246:247] op_sel_hi:[1,0]
	v_pk_mul_f32 v[50:51], v[50:51], v[246:247] op_sel_hi:[1,0]
	v_cvt_pk_bf16_f32 v48, v48, v49
	v_cvt_pk_bf16_f32 v49, v50, v51
	global_store_dwordx2 v250, v[48:49], s[20:21] offset:0
	v_pk_mul_f32 v[52:53], v[52:53], v[246:247] op_sel_hi:[1,0]
	v_pk_mul_f32 v[54:55], v[54:55], v[246:247] op_sel_hi:[1,0]
	v_cvt_pk_bf16_f32 v52, v52, v53
	v_cvt_pk_bf16_f32 v53, v54, v55
	global_store_dwordx2 v250, v[52:53], s[20:21] offset:16
	v_pk_mul_f32 v[56:57], v[56:57], v[246:247] op_sel_hi:[1,0]
	v_pk_mul_f32 v[58:59], v[58:59], v[246:247] op_sel_hi:[1,0]
	v_cvt_pk_bf16_f32 v56, v56, v57
	v_cvt_pk_bf16_f32 v57, v58, v59
	global_store_dwordx2 v250, v[56:57], s[20:21] offset:32
	v_pk_mul_f32 v[60:61], v[60:61], v[246:247] op_sel_hi:[1,0]
	v_pk_mul_f32 v[62:63], v[62:63], v[246:247] op_sel_hi:[1,0]
	v_cvt_pk_bf16_f32 v60, v60, v61
	v_cvt_pk_bf16_f32 v61, v62, v63
	global_store_dwordx2 v250, v[60:61], s[20:21] offset:48
	v_pk_mul_f32 v[64:65], v[64:65], v[246:247] op_sel_hi:[1,0]
	v_pk_mul_f32 v[66:67], v[66:67], v[246:247] op_sel_hi:[1,0]
	v_cvt_pk_bf16_f32 v64, v64, v65
	v_cvt_pk_bf16_f32 v65, v66, v67
	global_store_dwordx2 v250, v[64:65], s[20:21] offset:64
	v_pk_mul_f32 v[68:69], v[68:69], v[246:247] op_sel_hi:[1,0]
	v_pk_mul_f32 v[70:71], v[70:71], v[246:247] op_sel_hi:[1,0]
	v_cvt_pk_bf16_f32 v68, v68, v69
	v_cvt_pk_bf16_f32 v69, v70, v71
	global_store_dwordx2 v250, v[68:69], s[20:21] offset:80
	v_pk_mul_f32 v[72:73], v[72:73], v[246:247] op_sel_hi:[1,0]
	v_pk_mul_f32 v[74:75], v[74:75], v[246:247] op_sel_hi:[1,0]
	v_cvt_pk_bf16_f32 v72, v72, v73
	v_cvt_pk_bf16_f32 v73, v74, v75
	global_store_dwordx2 v250, v[72:73], s[20:21] offset:96
	v_pk_mul_f32 v[76:77], v[76:77], v[246:247] op_sel_hi:[1,0]
	v_pk_mul_f32 v[78:79], v[78:79], v[246:247] op_sel_hi:[1,0]
	v_cvt_pk_bf16_f32 v76, v76, v77
	v_cvt_pk_bf16_f32 v77, v78, v79
	global_store_dwordx2 v250, v[76:77], s[20:21] offset:112
	v_pk_mul_f32 v[80:81], v[80:81], v[246:247] op_sel_hi:[1,0]
	v_pk_mul_f32 v[82:83], v[82:83], v[246:247] op_sel_hi:[1,0]
	v_cvt_pk_bf16_f32 v80, v80, v81
	v_cvt_pk_bf16_f32 v81, v82, v83
	global_store_dwordx2 v250, v[80:81], s[20:21] offset:128
	v_pk_mul_f32 v[84:85], v[84:85], v[246:247] op_sel_hi:[1,0]
	v_pk_mul_f32 v[86:87], v[86:87], v[246:247] op_sel_hi:[1,0]
	v_cvt_pk_bf16_f32 v84, v84, v85
	v_cvt_pk_bf16_f32 v85, v86, v87
	global_store_dwordx2 v250, v[84:85], s[20:21] offset:144
	v_pk_mul_f32 v[88:89], v[88:89], v[246:247] op_sel_hi:[1,0]
	v_pk_mul_f32 v[90:91], v[90:91], v[246:247] op_sel_hi:[1,0]
	v_cvt_pk_bf16_f32 v88, v88, v89
	v_cvt_pk_bf16_f32 v89, v90, v91
	global_store_dwordx2 v250, v[88:89], s[20:21] offset:160
	v_pk_mul_f32 v[92:93], v[92:93], v[246:247] op_sel_hi:[1,0]
	v_pk_mul_f32 v[94:95], v[94:95], v[246:247] op_sel_hi:[1,0]
	v_cvt_pk_bf16_f32 v92, v92, v93
	v_cvt_pk_bf16_f32 v93, v94, v95
	global_store_dwordx2 v250, v[92:93], s[20:21] offset:176
	v_pk_mul_f32 v[96:97], v[96:97], v[246:247] op_sel_hi:[1,0]
	v_pk_mul_f32 v[98:99], v[98:99], v[246:247] op_sel_hi:[1,0]
	v_cvt_pk_bf16_f32 v96, v96, v97
	v_cvt_pk_bf16_f32 v97, v98, v99
	global_store_dwordx2 v250, v[96:97], s[20:21] offset:192
	v_pk_mul_f32 v[100:101], v[100:101], v[246:247] op_sel_hi:[1,0]
	v_pk_mul_f32 v[102:103], v[102:103], v[246:247] op_sel_hi:[1,0]
	v_cvt_pk_bf16_f32 v100, v100, v101
	v_cvt_pk_bf16_f32 v101, v102, v103
	global_store_dwordx2 v250, v[100:101], s[20:21] offset:208
	v_pk_mul_f32 v[104:105], v[104:105], v[246:247] op_sel_hi:[1,0]
	v_pk_mul_f32 v[106:107], v[106:107], v[246:247] op_sel_hi:[1,0]
	v_cvt_pk_bf16_f32 v104, v104, v105
	v_cvt_pk_bf16_f32 v105, v106, v107
	global_store_dwordx2 v250, v[104:105], s[20:21] offset:224
	v_pk_mul_f32 v[108:109], v[108:109], v[246:247] op_sel_hi:[1,0]
	v_pk_mul_f32 v[110:111], v[110:111], v[246:247] op_sel_hi:[1,0]
	v_cvt_pk_bf16_f32 v108, v108, v109
	v_cvt_pk_bf16_f32 v109, v110, v111
	global_store_dwordx2 v250, v[108:109], s[20:21] offset:240
	s_setprio 0
	v_mov_b32_e32 v133, 0
	s_waitcnt vmcnt(0)
	s_barrier
	s_and_saveexec_b64 s[0:1], s[24:25]
	s_cbranch_execz .LBB0_2592
	s_mov_b64 s[4:5], exec
	v_mbcnt_lo_u32_b32 v0, s4, 0
	v_mbcnt_hi_u32_b32 v0, s5, v0
	v_cmp_eq_u32_e32 vcc, 0, v0
	s_and_saveexec_b64 s[2:3], vcc
	s_cbranch_execz .LBB0_2591
	s_bcnt1_i32_b64 s4, s[4:5]
	v_mov_b32_e32 v1, s4
	global_atomic_add v1, v133, v1, s[34:35] sc0
	s_branch .LBB0_2591
